# v36 + norm-phase g/sc/sh load hoisting + layer-0 weight transposes moved from prologue into in-proj-0 tail idle WGs
# speedup vs baseline: 1.0047x; 1.0032x over previous
.LBB0_480:
	v_mul_f32_e32 v0, v23, v23
	v_mul_f32_e32 v14, v11, v11
	v_fmac_f32_e32 v0, v22, v22
	v_fmac_f32_e32 v14, v10, v10
	v_fmac_f32_e32 v0, v24, v24
	v_fmac_f32_e32 v14, v12, v12
	v_fmac_f32_e32 v0, v25, v25
	v_fmac_f32_e32 v14, v13, v13
	v_add_f32_e32 v0, v14, v0
	v_mul_f32_e32 v14, v7, v7
	v_fmac_f32_e32 v14, v6, v6
	v_fmac_f32_e32 v14, v8, v8
	v_fmac_f32_e32 v14, v9, v9
	v_add_f32_e32 v0, v14, v0
	v_mul_f32_e32 v14, v3, v3
	v_fmac_f32_e32 v14, v2, v2
	v_fmac_f32_e32 v14, v4, v4
	v_fmac_f32_e32 v14, v5, v5
	v_add_f32_e32 v0, v14, v0
	v_min_i32_e32 v14, 0x8000, v92
	v_ashrrev_i32_e32 v14, 12, v14
	v_mul_i32_i24_e32 v14, 0x1800, v14
	v_ashrrev_i32_e32 v15, 31, v14
	v_lshl_add_u64 v[20:21], v[14:15], 2, s[22:23]
	ds_bpermute_b32 v14, v108, v0
	v_lshl_add_u64 v[18:19], v[20:21], 0, s[10:11]
	v_mov_b32_e32 v85, v1
	v_lshl_add_u64 v[26:27], v[18:19], 0, v[84:85]
	global_load_dwordx4 v[28:31], v[26:27], off
	s_waitcnt lgkmcnt(0)
	v_add_f32_e32 v0, v0, v14
	ds_bpermute_b32 v14, v109, v0
	v_lshl_add_u64 v[26:27], v[20:21], 0, v[84:85]
	global_load_dwordx4 v[32:35], v[26:27], off
	v_ashrrev_i32_e32 v93, 31, v92
	v_lshlrev_b64 v[36:37], 11, v[92:93]
	s_waitcnt lgkmcnt(0)
	v_add_f32_e32 v0, v0, v14
	ds_bpermute_b32 v14, v110, v0
	v_mov_b32_e32 v87, v1
	v_mov_b32_e32 v89, v1
	v_mov_b32_e32 v91, v1
	s_waitcnt lgkmcnt(0)
	v_add_f32_e32 v0, v0, v14
	ds_bpermute_b32 v14, v111, v0
	s_waitcnt lgkmcnt(0)
	v_add_f32_e32 v0, v0, v14
	ds_bpermute_b32 v14, v112, v0
	s_waitcnt lgkmcnt(0)
	v_add_f32_e32 v0, v0, v14
	ds_bpermute_b32 v14, v113, v0
	s_waitcnt lgkmcnt(0)
	v_add_f32_e32 v0, v0, v14
	v_fmamk_f32 v0, v0, 0x3a800000, v218
	v_cmp_gt_f32_e32 vcc, s13, v0
	v_mul_f32_e32 v14, 0x4b800000, v0
	s_nop 0
	v_cndmask_b32_e32 v0, v0, v14, vcc
	v_rsq_f32_e32 v0, v0
	s_nop 0
	v_mul_f32_e32 v14, 0x45800000, v0
	v_cndmask_b32_e32 v0, v0, v14, vcc
	global_load_dwordx4 v[14:17], v[76:77], off
	v_mov_b32_e32 v87, v1
	v_mov_b32_e32 v89, v1
	v_mov_b32_e32 v91, v1
	global_load_dwordx4 v[168:171], v[76:77], off offset:1024
	v_lshl_add_u64 v[172:173], v[18:19], 0, v[86:87]
	global_load_dwordx4 v[172:175], v[172:173], off
	global_load_dwordx4 v[176:179], v[26:27], off offset:1024
	global_load_dwordx4 v[180:183], v[76:77], off offset:2048
	v_lshl_add_u64 v[184:185], v[18:19], 0, v[88:89]
	global_load_dwordx4 v[184:187], v[184:185], off
	global_load_dwordx4 v[188:191], v[26:27], off offset:2048
	global_load_dwordx4 v[192:195], v[76:77], off offset:3072
	v_lshl_add_u64 v[196:197], v[18:19], 0, v[90:91]
	global_load_dwordx4 v[196:199], v[196:197], off
	global_load_dwordx4 v[200:203], v[26:27], off offset:3072
	v_pk_mul_f32 v[20:21], v[24:25], v[0:1] op_sel_hi:[1,0]
	v_pk_mul_f32 v[22:23], v[22:23], v[0:1] op_sel_hi:[1,0]
	v_pk_mul_f32 v[12:13], v[12:13], v[0:1] op_sel_hi:[1,0]
	v_pk_mul_f32 v[10:11], v[10:11], v[0:1] op_sel_hi:[1,0]
	v_pk_mul_f32 v[8:9], v[8:9], v[0:1] op_sel_hi:[1,0]
	v_pk_mul_f32 v[6:7], v[6:7], v[0:1] op_sel_hi:[1,0]
	v_pk_mul_f32 v[4:5], v[4:5], v[0:1] op_sel_hi:[1,0]
	v_pk_mul_f32 v[2:3], v[2:3], v[0:1] op_sel_hi:[1,0]
	s_waitcnt vmcnt(9)
	v_pk_mul_f32 v[14:15], v[14:15], v[22:23]
	v_pk_mul_f32 v[16:17], v[16:17], v[20:21]
	v_pk_add_f32 v[20:21], v[30:31], 1.0 op_sel_hi:[1,0]
	v_pk_add_f32 v[22:23], v[28:29], 1.0 op_sel_hi:[1,0]
	v_pk_fma_f32 v[16:17], v[20:21], v[16:17], v[34:35]
	v_pk_fma_f32 v[14:15], v[22:23], v[14:15], v[32:33]
	v_lshl_add_u64 v[20:21], v[80:81], 0, v[36:37]
	v_cvt_pk_bf16_f32 v14, v14, v15
	v_cvt_pk_bf16_f32 v15, v16, v17
	global_store_dwordx2 v[20:21], v[14:15], off
	v_lshl_add_u64 v[22:23], v[18:19], 0, v[86:87]
	s_waitcnt vmcnt(7)
	v_pk_mul_f32 v[10:11], v[168:169], v[10:11]
	v_pk_mul_f32 v[12:13], v[170:171], v[12:13]
	v_pk_add_f32 v[14:15], v[174:175], 1.0 op_sel_hi:[1, 0]
	v_pk_add_f32 v[16:17], v[172:173], 1.0 op_sel_hi:[1, 0]
	v_pk_fma_f32 v[12:13], v[14:15], v[12:13], v[178:179]
	v_pk_fma_f32 v[10:11], v[16:17], v[10:11], v[176:177]
	v_lshl_add_u64 v[14:15], v[18:19], 0, v[88:89]
	v_cvt_pk_bf16_f32 v10, v10, v11
	v_cvt_pk_bf16_f32 v11, v12, v13
	global_store_dwordx2 v[20:21], v[10:11], off offset:512
	s_waitcnt vmcnt(5)
	v_pk_mul_f32 v[6:7], v[180:181], v[6:7]
	v_pk_mul_f32 v[8:9], v[182:183], v[8:9]
	v_pk_add_f32 v[10:11], v[186:187], 1.0 op_sel_hi:[1, 0]
	v_pk_add_f32 v[12:13], v[184:185], 1.0 op_sel_hi:[1, 0]
	v_pk_fma_f32 v[8:9], v[10:11], v[8:9], v[190:191]
	v_pk_fma_f32 v[6:7], v[12:13], v[6:7], v[188:189]
	v_lshl_add_u64 v[10:11], v[18:19], 0, v[90:91]
	v_cvt_pk_bf16_f32 v6, v6, v7
	v_cvt_pk_bf16_f32 v7, v8, v9
	global_store_dwordx2 v[20:21], v[6:7], off offset:1024
	s_waitcnt vmcnt(3)
	v_pk_mul_f32 v[2:3], v[2:3], v[192:193]
	v_pk_mul_f32 v[4:5], v[4:5], v[194:195]
	v_pk_add_f32 v[6:7], v[198:199], 1.0 op_sel_hi:[1, 0]
	v_pk_add_f32 v[8:9], v[196:197], 1.0 op_sel_hi:[1, 0]
	v_pk_fma_f32 v[4:5], v[4:5], v[6:7], v[202:203]
	v_pk_fma_f32 v[2:3], v[2:3], v[8:9], v[200:201]
	s_nop 0
	v_cvt_pk_bf16_f32 v2, v2, v3
	v_cvt_pk_bf16_f32 v3, v4, v5
	global_store_dwordx2 v[20:21], v[2:3], off offset:1536
	s_branch .LBB0_442
	s_nop 0
	s_nop 0
	s_nop 0
	s_nop 0
	s_nop 0
	s_nop 0
	s_nop 0
	s_nop 0
	s_nop 0
	s_nop 0
	s_nop 0
	s_nop 0

.LBB0_567:
	v_min_i32_e32 v0, 0x8000, v90
	v_ashrrev_i32_e32 v0, 12, v0
	v_mul_i32_i24_e32 v2, 0x1800, v0
	v_ashrrev_i32_e32 v3, 31, v2
	v_lshl_add_u64 v[10:11], v[2:3], 2, s[44:45]
	v_lshl_add_u64 v[14:15], v[10:11], 0, s[8:9]
	v_mov_b32_e32 v79, v1
	v_lshl_add_u64 v[6:7], v[14:15], 0, v[78:79]
	global_load_dwordx4 v[2:5], v[70:71], off
	v_lshl_add_u64 v[16:17], v[10:11], 0, v[78:79]
	global_load_dwordx4 v[6:9], v[6:7], off
	v_mul_f32_e32 v0, v63, v63
	global_load_dwordx4 v[10:13], v[16:17], off
	v_mov_b32_e32 v81, v1
	v_mov_b32_e32 v83, v1
	v_mov_b32_e32 v85, v1
	global_load_dwordx4 v[168:171], v[70:71], off offset:1024
	v_lshl_add_u64 v[172:173], v[14:15], 0, v[80:81]
	global_load_dwordx4 v[172:175], v[172:173], off
	global_load_dwordx4 v[176:179], v[16:17], off offset:1024
	global_load_dwordx4 v[180:183], v[70:71], off offset:2048
	v_lshl_add_u64 v[184:185], v[14:15], 0, v[82:83]
	global_load_dwordx4 v[184:187], v[184:185], off
	global_load_dwordx4 v[188:191], v[16:17], off offset:2048
	global_load_dwordx4 v[192:195], v[70:71], off offset:3072
	v_lshl_add_u64 v[196:197], v[14:15], 0, v[84:85]
	global_load_dwordx4 v[196:199], v[196:197], off
	global_load_dwordx4 v[200:203], v[16:17], off offset:3072
	v_mul_f32_e32 v18, v59, v59
	v_mul_f32_e32 v19, v55, v55
	v_fmac_f32_e32 v0, v62, v62
	v_fmac_f32_e32 v18, v58, v58
	v_mul_f32_e32 v20, v51, v51
	v_fmac_f32_e32 v19, v54, v54
	v_fmac_f32_e32 v0, v64, v64
	v_fmac_f32_e32 v18, v60, v60
	v_fmac_f32_e32 v20, v50, v50
	v_fmac_f32_e32 v19, v56, v56
	v_fmac_f32_e32 v0, v65, v65
	v_fmac_f32_e32 v18, v61, v61
	v_fmac_f32_e32 v20, v52, v52
	v_fmac_f32_e32 v19, v57, v57
	v_add_f32_e32 v0, v18, v0
	v_fmac_f32_e32 v20, v53, v53
	v_add_f32_e32 v0, v19, v0
	v_add_f32_e32 v0, v20, v0
	ds_bpermute_b32 v18, v102, v0
	v_ashrrev_i32_e32 v91, 31, v90
	v_mov_b32_e32 v81, v1
	v_mov_b32_e32 v83, v1
	v_mov_b32_e32 v85, v1
	s_waitcnt lgkmcnt(0)
	v_add_f32_e32 v0, v0, v18
	ds_bpermute_b32 v18, v103, v0
	s_waitcnt lgkmcnt(0)
	v_add_f32_e32 v0, v0, v18
	ds_bpermute_b32 v18, v104, v0
	s_waitcnt lgkmcnt(0)
	v_add_f32_e32 v0, v0, v18
	ds_bpermute_b32 v18, v105, v0
	s_waitcnt lgkmcnt(0)
	v_add_f32_e32 v0, v0, v18
	ds_bpermute_b32 v18, v106, v0
	s_waitcnt lgkmcnt(0)
	v_add_f32_e32 v0, v0, v18
	ds_bpermute_b32 v18, v107, v0
	s_waitcnt lgkmcnt(0)
	v_add_f32_e32 v0, v0, v18
	v_fmamk_f32 v0, v0, 0x3a800000, v218
	v_mul_f32_e32 v18, 0x4b800000, v0
	v_cmp_gt_f32_e32 vcc, s13, v0
	s_waitcnt vmcnt(10)
	v_pk_add_f32 v[8:9], v[8:9], 1.0 op_sel_hi:[1,0]
	v_cndmask_b32_e32 v0, v0, v18, vcc
	v_rsq_f32_e32 v0, v0
	v_pk_add_f32 v[6:7], v[6:7], 1.0 op_sel_hi:[1,0]
	v_lshlrev_b64 v[18:19], 11, v[90:91]
	v_lshl_add_u64 v[18:19], v[74:75], 0, v[18:19]
	v_mul_f32_e32 v20, 0x45800000, v0
	v_cndmask_b32_e32 v0, v0, v20, vcc
	v_pk_mul_f32 v[20:21], v[64:65], v[0:1] op_sel_hi:[1,0]
	v_pk_mul_f32 v[22:23], v[62:63], v[0:1] op_sel_hi:[1,0]
	v_pk_mul_f32 v[4:5], v[4:5], v[20:21]
	v_pk_mul_f32 v[2:3], v[2:3], v[22:23]
	s_waitcnt vmcnt(9)
	v_pk_fma_f32 v[4:5], v[8:9], v[4:5], v[12:13]
	v_pk_fma_f32 v[2:3], v[6:7], v[2:3], v[10:11]
	v_lshl_add_u64 v[6:7], v[14:15], 0, v[80:81]
	v_cvt_pk_bf16_f32 v2, v2, v3
	v_cvt_pk_bf16_f32 v3, v4, v5
	global_store_dwordx2 v[18:19], v[2:3], off
	v_pk_mul_f32 v[20:21], v[60:61], v[0:1] op_sel_hi:[1,0]
	v_pk_mul_f32 v[22:23], v[58:59], v[0:1] op_sel_hi:[1,0]
	s_waitcnt vmcnt(7)
	v_pk_add_f32 v[8:9], v[174:175], 1.0 op_sel_hi:[1, 0]
	v_pk_mul_f32 v[2:3], v[168:169], v[22:23]
	v_pk_mul_f32 v[4:5], v[170:171], v[20:21]
	v_pk_add_f32 v[6:7], v[172:173], 1.0 op_sel_hi:[1, 0]
	v_pk_fma_f32 v[4:5], v[8:9], v[4:5], v[178:179]
	v_pk_fma_f32 v[2:3], v[6:7], v[2:3], v[176:177]
	v_lshl_add_u64 v[6:7], v[14:15], 0, v[82:83]
	v_cvt_pk_bf16_f32 v2, v2, v3
	v_cvt_pk_bf16_f32 v3, v4, v5
	global_store_dwordx2 v[18:19], v[2:3], off offset:512
	v_pk_mul_f32 v[20:21], v[56:57], v[0:1] op_sel_hi:[1,0]
	v_pk_mul_f32 v[22:23], v[54:55], v[0:1] op_sel_hi:[1,0]
	s_waitcnt vmcnt(5)
	v_pk_add_f32 v[8:9], v[186:187], 1.0 op_sel_hi:[1, 0]
	v_pk_mul_f32 v[2:3], v[180:181], v[22:23]
	v_pk_mul_f32 v[4:5], v[182:183], v[20:21]
	v_pk_add_f32 v[6:7], v[184:185], 1.0 op_sel_hi:[1, 0]
	v_pk_fma_f32 v[4:5], v[8:9], v[4:5], v[190:191]
	v_pk_fma_f32 v[2:3], v[6:7], v[2:3], v[188:189]
	v_lshl_add_u64 v[6:7], v[14:15], 0, v[84:85]
	v_cvt_pk_bf16_f32 v2, v2, v3
	v_cvt_pk_bf16_f32 v3, v4, v5
	global_store_dwordx2 v[18:19], v[2:3], off offset:1024
	v_pk_mul_f32 v[14:15], v[52:53], v[0:1] op_sel_hi:[1,0]
	v_pk_mul_f32 v[16:17], v[50:51], v[0:1] op_sel_hi:[1,0]
	s_waitcnt vmcnt(3)
	v_pk_add_f32 v[8:9], v[198:199], 1.0 op_sel_hi:[1, 0]
	v_pk_mul_f32 v[2:3], v[16:17], v[192:193]
	v_pk_mul_f32 v[4:5], v[14:15], v[194:195]
	v_pk_add_f32 v[6:7], v[196:197], 1.0 op_sel_hi:[1, 0]
	v_pk_fma_f32 v[4:5], v[4:5], v[8:9], v[202:203]
	v_pk_fma_f32 v[2:3], v[2:3], v[6:7], v[200:201]
	s_nop 0
	v_cvt_pk_bf16_f32 v2, v2, v3
	v_cvt_pk_bf16_f32 v3, v4, v5
	global_store_dwordx2 v[18:19], v[2:3], off offset:1536
	s_branch .LBB0_529
